# mode-A epilogue: 15 Z loads and 13 sub-LN gain loads issued up front (vmcnt re-derived), previously one group ahead
# baseline (speedup 1.0000x reference)
; #define LAS __attribute__((address_space(3)))
; template <int DQK, int DV, int MODE>
; __device__ __forceinline__ void attn_item(LAS unsigned char* lds, int item, const AttnCtx& cx) {
;     ...
;         if (hf == 0) {
;             float ss = 0.f;
;             const float lam = cx.lamp[cx.layer], oml = cx.lamp[2 + cx.layer];
; #pragma unroll
;             for (int d = 0; d < NDV; ++d)
; #pragma unroll
;                 for (int g4 = 0; g4 < 4; ++g4) {
;                     const f32x4 o2 = *(LAS const f32x4*)(X + (32 * wq + r) * 132 + 32 * d + 8 * g4 + 4 * h);
; #pragma unroll
;                     for (int e = 0; e < 4; ++e) { const float o = O[d][4 * g4 + e] * inv - lam * o2[e]; O[d][4 * g4 + e] = o; ss += o * o; }
;                 }
;             ss += __shfl_xor(ss, 32);
;             const float rstd = rsqrtf(ss * (1.f / 128.f) + EPS) * oml;
; #pragma unroll
;             for (int d = 0; d < NDV; ++d)
; #pragma unroll
;                 for (int g4 = 0; g4 < 4; ++g4) {
;                     const int dv = 32 * d + 8 * g4 + 4 * h;
;                     const f32x4 gn = *(const f32x4*)(cx.subln + dv);
;                     const u32x2 sz = *(const u32x2*)(P + (size_t)qtok * NIN + COL_Z + head * 128 + dv);
.LBB0_270:
	s_cmpk_gt_u32 s37, 0xff
	s_waitcnt lgkmcnt(0)
	s_barrier
	s_cbranch_scc1 .LBB0_159
	v_lshl_or_b32 v66, s81, 5, v201
	s_movk_i32 s3, 0x210
	s_lshl_b32 s48, s31, 1
	v_mul_lo_u32 v68, v66, s3
	v_lshl_add_u64 v[66:67], v[182:183], 0, s[48:49]
	v_add3_u32 v74, 0, v68, v0
	v_lshlrev_b32_e32 v0, 1, v200
	v_lshl_add_u64 v[134:135], v[66:67], 0, v[0:1]
	s_movk_i32 s3, 0x3000
	v_add_co_u32_e32 v66, vcc, s3, v134
	global_load_dword v142, v[178:179], off
	s_nop 0
	v_addc_co_u32_e32 v67, vcc, 0, v135, vcc
	global_load_dwordx2 v[138:139], v[66:67], off offset:3072
	global_load_dword v143, v[178:179], off offset:8
	v_and_b32_e32 v66, 64, v219
	v_xor_b32_e32 v70, 32, v219
	v_add_u32_e32 v71, 64, v66
	v_lshlrev_b32_e32 v137, 2, v200
	v_cmp_lt_i32_e32 vcc, v70, v71
	global_load_dwordx4 v[66:69], v137, s[0:1]
	s_mov_b32 s3, 0x800000
	v_cndmask_b32_e32 v144, v219, v70, vcc
	ds_read_b128 v[126:129], v74
	ds_read_b128 v[122:125], v74 offset:32
	ds_read_b128 v[118:121], v74 offset:64
	ds_read_b128 v[114:117], v74 offset:96
	ds_read_b128 v[110:113], v74 offset:128
	ds_read_b128 v[106:109], v74 offset:160
	ds_read_b128 v[102:105], v74 offset:192
	ds_read_b128 v[98:101], v74 offset:224
	ds_read_b128 v[94:97], v74 offset:256
	ds_read_b128 v[90:93], v74 offset:288
	ds_read_b128 v[86:89], v74 offset:320
	ds_read_b128 v[82:85], v74 offset:352
	ds_read_b128 v[70:73], v74 offset:448
	ds_read_b128 v[130:133], v74 offset:480
	ds_read_b128 v[78:81], v74 offset:384
	ds_read_b128 v[74:77], v74 offset:416
	v_lshlrev_b32_e32 v144, 2, v144
	v_readlane_b32 s4, v254, 26
	v_lshlrev_b64 v[140:141], 10, v[180:181]
	v_readlane_b32 s5, v254, 27
	s_mov_b64 s[22:23], 0x3c00
	v_lshl_add_u64 v[134:135], v[134:135], 0, s[22:23]
	global_load_dwordx2 v[156:157], v[134:135], off offset:16
	global_load_dwordx4 v[192:195], v137, s[0:1] offset:32
	global_load_dwordx2 v[158:159], v[134:135], off offset:32
	global_load_dwordx4 v[196:199], v137, s[0:1] offset:64
	global_load_dwordx2 v[160:161], v[134:135], off offset:48
	global_load_dwordx4 v[202:205], v137, s[0:1] offset:96
	global_load_dwordx2 v[162:163], v[134:135], off offset:64
	global_load_dwordx4 v[206:209], v137, s[0:1] offset:128
	global_load_dwordx2 v[164:165], v[134:135], off offset:80
	global_load_dwordx4 v[210:213], v137, s[0:1] offset:160
	global_load_dwordx2 v[166:167], v[134:135], off offset:96
	global_load_dwordx4 v[214:217], v137, s[0:1] offset:192
	global_load_dwordx2 v[168:169], v[134:135], off offset:112
	global_load_dwordx4 v[222:225], v137, s[0:1] offset:224
	global_load_dwordx2 v[170:171], v[134:135], off offset:128
	global_load_dwordx4 v[226:229], v137, s[0:1] offset:256
	global_load_dwordx2 v[172:173], v[134:135], off offset:144
	global_load_dwordx4 v[230:233], v137, s[0:1] offset:288
	global_load_dwordx2 v[174:175], v[134:135], off offset:160
	global_load_dwordx4 v[234:237], v137, s[0:1] offset:320
	global_load_dwordx2 v[176:177], v[134:135], off offset:176
	global_load_dwordx4 v[238:241], v137, s[0:1] offset:352
	global_load_dwordx2 v[184:185], v[134:135], off offset:192
	global_load_dwordx4 v[242:245], v137, s[0:1] offset:384
	global_load_dwordx2 v[186:187], v[134:135], off offset:208
	global_load_dwordx4 v[246:249], v137, s[0:1] offset:416
	global_load_dwordx2 v[188:189], v[134:135], off offset:224
	global_load_dwordx2 v[190:191], v[134:135], off offset:240
	s_waitcnt vmcnt(30)
	v_lshlrev_b32_e32 v148, 16, v138
	s_waitcnt vmcnt(29) lgkmcnt(11)
	v_pk_mul_f32 v[110:111], v[142:143], v[110:111] op_sel_hi:[0,1]
	v_pk_fma_f32 v[110:111], v[136:137], v[34:35], v[110:111] op_sel_hi:[0,1,1] neg_lo:[0,0,1] neg_hi:[0,0,1]
	s_waitcnt lgkmcnt(8)
	v_pk_mul_f32 v[34:35], v[142:143], v[100:101] op_sel_hi:[0,1]
	v_pk_fma_f32 v[48:49], v[136:137], v[48:49], v[34:35] op_sel_hi:[0,1,1] neg_lo:[0,0,1] neg_hi:[0,0,1]
	v_pk_mul_f32 v[34:35], v[142:143], v[98:99] op_sel_hi:[0,1]
	v_pk_fma_f32 v[46:47], v[136:137], v[46:47], v[34:35] op_sel_hi:[0,1,1] neg_lo:[0,0,1] neg_hi:[0,0,1]
	s_waitcnt lgkmcnt(7)
	v_pk_mul_f32 v[34:35], v[142:143], v[96:97] op_sel_hi:[0,1]
	v_pk_fma_f32 v[96:97], v[136:137], v[20:21], v[34:35] op_sel_hi:[0,1,1] neg_lo:[0,0,1] neg_hi:[0,0,1]
	v_pk_mul_f32 v[20:21], v[142:143], v[94:95] op_sel_hi:[0,1]
	v_pk_fma_f32 v[94:95], v[136:137], v[18:19], v[20:21] op_sel_hi:[0,1,1] neg_lo:[0,0,1] neg_hi:[0,0,1]
	s_waitcnt lgkmcnt(6)
	v_pk_mul_f32 v[18:19], v[142:143], v[92:93] op_sel_hi:[0,1]
	v_pk_fma_f32 v[34:35], v[136:137], v[24:25], v[18:19] op_sel_hi:[0,1,1] neg_lo:[0,0,1] neg_hi:[0,0,1]
	v_pk_mul_f32 v[18:19], v[142:143], v[90:91] op_sel_hi:[0,1]
	v_pk_fma_f32 v[90:91], v[136:137], v[22:23], v[18:19] op_sel_hi:[0,1,1] neg_lo:[0,0,1] neg_hi:[0,0,1]
	s_waitcnt lgkmcnt(5)
	v_pk_mul_f32 v[18:19], v[142:143], v[88:89] op_sel_hi:[0,1]
	v_pk_fma_f32 v[28:29], v[136:137], v[28:29], v[18:19] op_sel_hi:[0,1,1] neg_lo:[0,0,1] neg_hi:[0,0,1]
	v_pk_mul_f32 v[18:19], v[142:143], v[86:87] op_sel_hi:[0,1]
	v_pk_fma_f32 v[26:27], v[136:137], v[26:27], v[18:19] op_sel_hi:[0,1,1] neg_lo:[0,0,1] neg_hi:[0,0,1]
	s_waitcnt lgkmcnt(4)
	v_pk_mul_f32 v[18:19], v[142:143], v[84:85] op_sel_hi:[0,1]
	v_pk_fma_f32 v[22:23], v[136:137], v[32:33], v[18:19] op_sel_hi:[0,1,1] neg_lo:[0,0,1] neg_hi:[0,0,1]
	v_pk_mul_f32 v[18:19], v[142:143], v[82:83] op_sel_hi:[0,1]
	v_pk_mul_f32 v[126:127], v[142:143], v[126:127] op_sel_hi:[0,1]
	v_pk_fma_f32 v[24:25], v[136:137], v[30:31], v[18:19] op_sel_hi:[0,1,1] neg_lo:[0,0,1] neg_hi:[0,0,1]
	s_waitcnt lgkmcnt(1)
; #define LAS __attribute__((address_space(3)))
; template <int DQK, int DV, int MODE>
; __device__ __forceinline__ void attn_item(LAS unsigned char* lds, int item, const AttnCtx& cx) {
;     ...
;             for (int d = 0; d < NDV; ++d)
; #pragma unroll
;                 for (int g4 = 0; g4 < 4; ++g4) {
;                     const f32x4 o2 = *(LAS const f32x4*)(X + (32 * wq + r) * 132 + 32 * d + 8 * g4 + 4 * h);
; #pragma unroll
;                     for (int e = 0; e < 4; ++e) { const float o = O[d][4 * g4 + e] * inv - lam * o2[e]; O[d][4 * g4 + e] = o; ss += o * o; }
;                 }
;             ss += __shfl_xor(ss, 32);
	v_pk_mul_f32 v[18:19], v[142:143], v[80:81] op_sel_hi:[0,1]
	v_pk_mul_f32 v[128:129], v[142:143], v[128:129] op_sel_hi:[0,1]
	v_pk_mul_f32 v[112:113], v[142:143], v[112:113] op_sel_hi:[0,1]
	v_pk_fma_f32 v[50:51], v[136:137], v[50:51], v[126:127] op_sel_hi:[0,1,1] neg_lo:[0,0,1] neg_hi:[0,0,1]
	v_pk_fma_f32 v[18:19], v[136:137], v[4:5], v[18:19] op_sel_hi:[0,1,1] neg_lo:[0,0,1] neg_hi:[0,0,1]
	v_pk_mul_f32 v[4:5], v[142:143], v[78:79] op_sel_hi:[0,1]
	v_pk_mul_f32 v[108:109], v[142:143], v[108:109] op_sel_hi:[0,1]
	v_pk_fma_f32 v[52:53], v[136:137], v[52:53], v[128:129] op_sel_hi:[0,1,1] neg_lo:[0,0,1] neg_hi:[0,0,1]
	v_pk_fma_f32 v[36:37], v[136:137], v[36:37], v[112:113] op_sel_hi:[0,1,1] neg_lo:[0,0,1] neg_hi:[0,0,1]
	v_pk_mul_f32 v[112:113], v[50:51], v[50:51]
	v_pk_fma_f32 v[20:21], v[136:137], v[2:3], v[4:5] op_sel_hi:[0,1,1] neg_lo:[0,0,1] neg_hi:[0,0,1]
	s_waitcnt lgkmcnt(0)
	v_pk_mul_f32 v[2:3], v[142:143], v[76:77] op_sel_hi:[0,1]
	v_pk_mul_f32 v[122:123], v[142:143], v[122:123] op_sel_hi:[0,1]
	v_pk_fma_f32 v[40:41], v[136:137], v[40:41], v[108:109] op_sel_hi:[0,1,1] neg_lo:[0,0,1] neg_hi:[0,0,1]
	v_pk_mul_f32 v[108:109], v[52:53], v[52:53]
	v_pk_fma_f32 v[2:3], v[136:137], v[8:9], v[2:3] op_sel_hi:[0,1,1] neg_lo:[0,0,1] neg_hi:[0,0,1]
	v_pk_mul_f32 v[8:9], v[142:143], v[70:71] op_sel_hi:[0,1]
	v_add_f32_e32 v70, v112, v113
	v_pk_mul_f32 v[116:117], v[142:143], v[116:117] op_sel_hi:[0,1]
	v_pk_fma_f32 v[54:55], v[136:137], v[54:55], v[122:123] op_sel_hi:[0,1,1] neg_lo:[0,0,1] neg_hi:[0,0,1]
	v_add_f32_e32 v70, v108, v70
	v_pk_mul_f32 v[124:125], v[142:143], v[124:125] op_sel_hi:[0,1]
	v_pk_fma_f32 v[64:65], v[136:137], v[64:65], v[116:117] op_sel_hi:[0,1,1] neg_lo:[0,0,1] neg_hi:[0,0,1]
	v_pk_mul_f32 v[116:117], v[54:55], v[54:55]
	v_add_f32_e32 v70, v109, v70
	v_pk_mul_f32 v[114:115], v[142:143], v[114:115] op_sel_hi:[0,1]
	v_pk_fma_f32 v[56:57], v[136:137], v[56:57], v[124:125] op_sel_hi:[0,1,1] neg_lo:[0,0,1] neg_hi:[0,0,1]
	v_add_f32_e32 v70, v116, v70
	v_pk_mul_f32 v[118:119], v[142:143], v[118:119] op_sel_hi:[0,1]
	v_pk_fma_f32 v[62:63], v[136:137], v[62:63], v[114:115] op_sel_hi:[0,1,1] neg_lo:[0,0,1] neg_hi:[0,0,1]
	v_pk_mul_f32 v[114:115], v[56:57], v[56:57]
	v_add_f32_e32 v70, v117, v70
	v_pk_mul_f32 v[120:121], v[142:143], v[120:121] op_sel_hi:[0,1]
	v_pk_fma_f32 v[58:59], v[136:137], v[58:59], v[118:119] op_sel_hi:[0,1,1] neg_lo:[0,0,1] neg_hi:[0,0,1]
	v_add_f32_e32 v70, v114, v70
	v_pk_fma_f32 v[60:61], v[136:137], v[60:61], v[120:121] op_sel_hi:[0,1,1] neg_lo:[0,0,1] neg_hi:[0,0,1]
	v_pk_mul_f32 v[120:121], v[58:59], v[58:59]
	v_add_f32_e32 v70, v115, v70
	v_add_f32_e32 v70, v120, v70
	v_pk_mul_f32 v[118:119], v[60:61], v[60:61]
	v_add_f32_e32 v70, v121, v70
	v_add_f32_e32 v70, v118, v70
	v_pk_mul_f32 v[124:125], v[62:63], v[62:63]
	v_add_f32_e32 v70, v119, v70
	v_add_f32_e32 v70, v124, v70
	v_pk_mul_f32 v[122:123], v[64:65], v[64:65]
	v_add_f32_e32 v70, v125, v70
	v_add_f32_e32 v70, v122, v70
	v_pk_mul_f32 v[128:129], v[110:111], v[110:111]
	v_add_f32_e32 v70, v123, v70
	v_add_f32_e32 v70, v128, v70
	v_pk_mul_f32 v[106:107], v[142:143], v[106:107] op_sel_hi:[0,1]
	v_pk_mul_f32 v[126:127], v[36:37], v[36:37]
	v_add_f32_e32 v70, v129, v70
	v_pk_mul_f32 v[132:133], v[142:143], v[132:133] op_sel_hi:[0,1]
	v_pk_fma_f32 v[38:39], v[136:137], v[38:39], v[106:107] op_sel_hi:[0,1,1] neg_lo:[0,0,1] neg_hi:[0,0,1]
	v_add_f32_e32 v70, v126, v70
	v_pk_fma_f32 v[16:17], v[136:137], v[16:17], v[132:133] op_sel_hi:[0,1,1] neg_lo:[0,0,1] neg_hi:[0,0,1]
	v_pk_mul_f32 v[132:133], v[38:39], v[38:39]
	v_add_f32_e32 v70, v127, v70
	v_pk_mul_f32 v[130:131], v[142:143], v[130:131] op_sel_hi:[0,1]
	v_add_f32_e32 v70, v132, v70
	v_pk_mul_f32 v[102:103], v[142:143], v[102:103] op_sel_hi:[0,1]
	v_pk_fma_f32 v[14:15], v[136:137], v[14:15], v[130:131] op_sel_hi:[0,1,1] neg_lo:[0,0,1] neg_hi:[0,0,1]
	v_pk_mul_f32 v[130:131], v[40:41], v[40:41]
	v_add_f32_e32 v70, v133, v70
	v_pk_fma_f32 v[42:43], v[136:137], v[42:43], v[102:103] op_sel_hi:[0,1,1] neg_lo:[0,0,1] neg_hi:[0,0,1]
	v_add_f32_e32 v70, v130, v70
	v_pk_mul_f32 v[104:105], v[142:143], v[104:105] op_sel_hi:[0,1]
	v_pk_mul_f32 v[102:103], v[42:43], v[42:43]
	v_add_f32_e32 v70, v131, v70
	v_pk_fma_f32 v[44:45], v[136:137], v[44:45], v[104:105] op_sel_hi:[0,1,1] neg_lo:[0,0,1] neg_hi:[0,0,1]
	v_add_f32_e32 v70, v102, v70
	v_pk_mul_f32 v[146:147], v[44:45], v[44:45]
	v_add_f32_e32 v70, v103, v70
	v_add_f32_e32 v70, v146, v70
	v_pk_mul_f32 v[98:99], v[46:47], v[46:47]
	v_add_f32_e32 v70, v147, v70
	v_add_f32_e32 v70, v98, v70
	v_pk_mul_f32 v[100:101], v[48:49], v[48:49]
	v_add_f32_e32 v70, v99, v70
	v_add_f32_e32 v70, v100, v70
	v_pk_mul_f32 v[152:153], v[94:95], v[94:95]
	v_add_f32_e32 v70, v101, v70
	v_add_f32_e32 v70, v152, v70
	v_pk_mul_f32 v[150:151], v[96:97], v[96:97]
	v_add_f32_e32 v70, v153, v70
	v_add_f32_e32 v70, v150, v70
	v_pk_mul_f32 v[154:155], v[90:91], v[90:91]
	v_add_f32_e32 v70, v151, v70
	v_add_f32_e32 v70, v154, v70
	v_pk_mul_f32 v[92:93], v[34:35], v[34:35]
	v_add_f32_e32 v70, v155, v70
	v_add_f32_e32 v70, v92, v70
	v_pk_mul_f32 v[86:87], v[26:27], v[26:27]
	v_add_f32_e32 v70, v93, v70
	v_add_f32_e32 v70, v86, v70
	v_pk_mul_f32 v[88:89], v[28:29], v[28:29]
	v_add_f32_e32 v70, v87, v70
	v_add_f32_e32 v70, v88, v70
	v_pk_mul_f32 v[30:31], v[24:25], v[24:25]
	v_add_f32_e32 v70, v89, v70
	v_add_f32_e32 v30, v30, v70
	v_pk_mul_f32 v[32:33], v[22:23], v[22:23]
	v_add_f32_e32 v30, v31, v30
	v_add_f32_e32 v30, v32, v30
	v_pk_mul_f32 v[78:79], v[20:21], v[20:21]
	v_add_f32_e32 v30, v33, v30
	v_add_f32_e32 v30, v78, v30
	v_pk_mul_f32 v[80:81], v[18:19], v[18:19]
	v_pk_mul_f32 v[4:5], v[142:143], v[74:75] op_sel_hi:[0,1]
	v_add_f32_e32 v30, v79, v30
	v_pk_fma_f32 v[4:5], v[136:137], v[6:7], v[4:5] op_sel_hi:[0,1,1] neg_lo:[0,0,1] neg_hi:[0,0,1]
	v_add_f32_e32 v30, v80, v30
	v_pk_mul_f32 v[74:75], v[4:5], v[4:5]
	v_add_f32_e32 v30, v81, v30
	v_add_f32_e32 v30, v74, v30
	v_pk_mul_f32 v[76:77], v[2:3], v[2:3]
	v_add_f32_e32 v30, v75, v30
	v_pk_fma_f32 v[8:9], v[136:137], v[10:11], v[8:9] op_sel_hi:[0,1,1] neg_lo:[0,0,1] neg_hi:[0,0,1]
	v_add_f32_e32 v30, v76, v30
	v_pk_mul_f32 v[6:7], v[142:143], v[72:73] op_sel_hi:[0,1]
	v_pk_mul_f32 v[10:11], v[8:9], v[8:9]
	v_add_f32_e32 v30, v77, v30
	v_pk_fma_f32 v[6:7], v[136:137], v[12:13], v[6:7] op_sel_hi:[0,1,1] neg_lo:[0,0,1] neg_hi:[0,0,1]
	v_add_f32_e32 v10, v10, v30
	v_pk_mul_f32 v[12:13], v[6:7], v[6:7]
	v_add_f32_e32 v10, v11, v10
	v_add_f32_e32 v10, v12, v10
	v_pk_mul_f32 v[104:105], v[14:15], v[14:15]
	v_add_f32_e32 v10, v13, v10
	v_add_f32_e32 v10, v104, v10
	v_pk_mul_f32 v[106:107], v[16:17], v[16:17]
	v_add_f32_e32 v10, v105, v10
	v_add_f32_e32 v10, v106, v10
	v_add_f32_e32 v30, v107, v10
	ds_bpermute_b32 v31, v144, v30
	v_lshl_add_u64 v[10:11], s[4:5], 0, v[140:141]
	v_lshl_add_u64 v[10:11], v[10:11], 0, s[48:49]
	v_lshl_add_u64 v[10:11], v[10:11], 0, v[0:1]
	v_and_b32_e32 v149, 0xffff0000, v138
	s_waitcnt lgkmcnt(0)
; __device__ __forceinline__ unsigned pk2(float lo, float hi) { f32x2 v = {lo, hi}; bf16x2_t b = __builtin_convertvector(v, bf16x2_t); return __builtin_bit_cast(unsigned, b); }
; __device__ __forceinline__ float bflo(unsigned u) { return __uint_as_float(u << 16); }
; __device__ __forceinline__ float bfhi(unsigned u) { return __uint_as_float(u & 0xffff0000u); }
; template <int DQK, int DV, int MODE>
; __device__ __forceinline__ void attn_item(LAS unsigned char* lds, int item, const AttnCtx& cx) {
;     ...
;             const float rstd = rsqrtf(ss * (1.f / 128.f) + EPS) * oml;
; #pragma unroll
;             for (int d = 0; d < NDV; ++d)
; #pragma unroll
;                 for (int g4 = 0; g4 < 4; ++g4) {
;                     const int dv = 32 * d + 8 * g4 + 4 * h;
;                     const f32x4 gn = *(const f32x4*)(cx.subln + dv);
;                     const u32x2 sz = *(const u32x2*)(P + (size_t)qtok * NIN + COL_Z + head * 128 + dv);
;                     u32x2 o;
;                     o.x = pk2(O[d][4 * g4] * rstd * gn[0] * bflo(sz.x), O[d][4 * g4 + 1] * rstd * gn[1] * bfhi(sz.x));
;                     o.y = pk2(O[d][4 * g4 + 2] * rstd * gn[2] * bflo(sz.y), O[d][4 * g4 + 3] * rstd * gn[3] * bfhi(sz.y));
;                     *(u32x2*)(cx.T + (size_t)qtok * 512 + head * 128 + dv) = o;
;                 }
	v_add_f32_e32 v30, v30, v31
	v_fmamk_f32 v30, v30, 0x3c000000, v218
	v_mul_f32_e32 v31, 0x4b800000, v30
	v_cmp_gt_f32_e32 vcc, s3, v30
	v_lshlrev_b32_e32 v12, 16, v139
	v_and_b32_e32 v13, 0xffff0000, v139
	v_cndmask_b32_e32 v30, v30, v31, vcc
	v_rsq_f32_e32 v30, v30
	v_mul_f32_e32 v0, 0x45800000, v30
	v_cndmask_b32_e32 v0, v30, v0, vcc
	v_mul_f32_e32 v0, v143, v0
	v_pk_mul_f32 v[30:31], v[50:51], v[0:1] op_sel_hi:[1,0]
	v_pk_mul_f32 v[32:33], v[52:53], v[0:1] op_sel_hi:[1,0]
	s_waitcnt vmcnt(28)
	v_pk_mul_f32 v[30:31], v[66:67], v[30:31]
	v_pk_mul_f32 v[32:33], v[68:69], v[32:33]
	v_pk_mul_f32 v[30:31], v[30:31], v[148:149]
	v_pk_mul_f32 v[12:13], v[32:33], v[12:13]
	v_cvt_pk_bf16_f32 v30, v30, v31
	v_cvt_pk_bf16_f32 v31, v12, v13
	global_store_dwordx2 v[10:11], v[30:31], off
	s_nop 0
	v_pk_mul_f32 v[54:55], v[54:55], v[0:1] op_sel_hi:[1,0]
	v_pk_mul_f32 v[56:57], v[56:57], v[0:1] op_sel_hi:[1,0]
	v_pk_mul_f32 v[36:37], v[36:37], v[0:1] op_sel_hi:[1,0]
	v_pk_mul_f32 v[38:39], v[38:39], v[0:1] op_sel_hi:[1,0]
	v_pk_mul_f32 v[40:41], v[40:41], v[0:1] op_sel_hi:[1,0]
	v_pk_mul_f32 v[34:35], v[34:35], v[0:1] op_sel_hi:[1,0]
	v_pk_mul_f32 v[26:27], v[26:27], v[0:1] op_sel_hi:[1,0]
	v_pk_mul_f32 v[28:29], v[28:29], v[0:1] op_sel_hi:[1,0]
	v_pk_mul_f32 v[24:25], v[24:25], v[0:1] op_sel_hi:[1,0]
	v_pk_mul_f32 v[22:23], v[22:23], v[0:1] op_sel_hi:[1,0]
	v_pk_mul_f32 v[20:21], v[20:21], v[0:1] op_sel_hi:[1,0]
	v_pk_mul_f32 v[18:19], v[18:19], v[0:1] op_sel_hi:[1,0]
	v_pk_mul_f32 v[4:5], v[4:5], v[0:1] op_sel_hi:[1,0]
	v_pk_mul_f32 v[2:3], v[2:3], v[0:1] op_sel_hi:[1,0]
	v_pk_mul_f32 v[8:9], v[8:9], v[0:1] op_sel_hi:[1,0]
	v_pk_mul_f32 v[6:7], v[6:7], v[0:1] op_sel_hi:[1,0]
	s_waitcnt vmcnt(28)
	v_lshlrev_b32_e32 v50, 16, v156
	v_and_b32_e32 v51, 0xffff0000, v156
	v_lshlrev_b32_e32 v52, 16, v157
	v_and_b32_e32 v53, 0xffff0000, v157
	s_waitcnt vmcnt(27)
	v_pk_mul_f32 v[192:193], v[192:193], v[54:55]
	v_pk_mul_f32 v[194:195], v[194:195], v[56:57]
	v_pk_mul_f32 v[192:193], v[192:193], v[50:51]
	v_pk_mul_f32 v[194:195], v[194:195], v[52:53]
	v_cvt_pk_bf16_f32 v192, v192, v193
	v_cvt_pk_bf16_f32 v193, v194, v195
	global_store_dwordx2 v[10:11], v[192:193], off offset:16
	s_nop 0
	v_pk_mul_f32 v[54:55], v[58:59], v[0:1] op_sel_hi:[1,0]
	v_pk_mul_f32 v[56:57], v[60:61], v[0:1] op_sel_hi:[1,0]
	s_waitcnt vmcnt(27)
	v_lshlrev_b32_e32 v52, 16, v158
	v_and_b32_e32 v53, 0xffff0000, v158
	v_lshlrev_b32_e32 v12, 16, v159
	v_and_b32_e32 v13, 0xffff0000, v159
	s_waitcnt vmcnt(26)
	v_pk_mul_f32 v[196:197], v[196:197], v[54:55]
	v_pk_mul_f32 v[198:199], v[198:199], v[56:57]
	v_pk_mul_f32 v[196:197], v[196:197], v[52:53]
	v_pk_mul_f32 v[12:13], v[198:199], v[12:13]
	v_cvt_pk_bf16_f32 v196, v196, v197
	v_cvt_pk_bf16_f32 v197, v12, v13
	global_store_dwordx2 v[10:11], v[196:197], off offset:32
	s_nop 0
	v_pk_mul_f32 v[54:55], v[62:63], v[0:1] op_sel_hi:[1,0]
	v_pk_mul_f32 v[56:57], v[64:65], v[0:1] op_sel_hi:[1,0]
	s_waitcnt vmcnt(26)
	v_lshlrev_b32_e32 v52, 16, v160
	v_and_b32_e32 v53, 0xffff0000, v160
	v_lshlrev_b32_e32 v50, 16, v161
	v_and_b32_e32 v51, 0xffff0000, v161
	s_waitcnt vmcnt(25)
	v_pk_mul_f32 v[202:203], v[202:203], v[54:55]
	v_pk_mul_f32 v[204:205], v[204:205], v[56:57]
	v_pk_mul_f32 v[202:203], v[202:203], v[52:53]
	v_pk_mul_f32 v[204:205], v[204:205], v[50:51]
	v_cvt_pk_bf16_f32 v202, v202, v203
	v_cvt_pk_bf16_f32 v203, v204, v205
	global_store_dwordx2 v[10:11], v[202:203], off offset:48
	s_nop 0
	v_pk_mul_f32 v[54:55], v[110:111], v[0:1] op_sel_hi:[1,0]
	s_waitcnt vmcnt(25)
	v_lshlrev_b32_e32 v52, 16, v162
	v_and_b32_e32 v53, 0xffff0000, v162
	v_lshlrev_b32_e32 v12, 16, v163
	v_and_b32_e32 v13, 0xffff0000, v163
	s_waitcnt vmcnt(24)
	v_pk_mul_f32 v[206:207], v[206:207], v[54:55]
	v_pk_mul_f32 v[208:209], v[208:209], v[36:37]
	v_pk_mul_f32 v[206:207], v[206:207], v[52:53]
	v_pk_mul_f32 v[12:13], v[208:209], v[12:13]
	v_cvt_pk_bf16_f32 v206, v206, v207
	v_cvt_pk_bf16_f32 v207, v12, v13
	global_store_dwordx2 v[10:11], v[206:207], off offset:64
	s_nop 0
	s_waitcnt vmcnt(24)
	v_lshlrev_b32_e32 v36, 16, v164
	v_and_b32_e32 v37, 0xffff0000, v164
	v_lshlrev_b32_e32 v50, 16, v165
	v_and_b32_e32 v51, 0xffff0000, v165
	s_waitcnt vmcnt(23)
	v_pk_mul_f32 v[210:211], v[210:211], v[38:39]
	v_pk_mul_f32 v[212:213], v[212:213], v[40:41]
	v_pk_mul_f32 v[210:211], v[210:211], v[36:37]
	v_pk_mul_f32 v[212:213], v[212:213], v[50:51]
	v_cvt_pk_bf16_f32 v210, v210, v211
	v_cvt_pk_bf16_f32 v211, v212, v213
	global_store_dwordx2 v[10:11], v[210:211], off offset:80
	s_nop 0
	v_pk_mul_f32 v[40:41], v[42:43], v[0:1] op_sel_hi:[1,0]
	v_pk_mul_f32 v[42:43], v[44:45], v[0:1] op_sel_hi:[1,0]
	s_waitcnt vmcnt(23)
	v_lshlrev_b32_e32 v38, 16, v166
	v_and_b32_e32 v39, 0xffff0000, v166
	v_lshlrev_b32_e32 v12, 16, v167
	v_and_b32_e32 v13, 0xffff0000, v167
	s_waitcnt vmcnt(22)
; __device__ __forceinline__ unsigned pk2(float lo, float hi) { f32x2 v = {lo, hi}; bf16x2_t b = __builtin_convertvector(v, bf16x2_t); return __builtin_bit_cast(unsigned, b); }
; __device__ __forceinline__ float bflo(unsigned u) { return __uint_as_float(u << 16); }
; __device__ __forceinline__ float bfhi(unsigned u) { return __uint_as_float(u & 0xffff0000u); }
; template <int DQK, int DV, int MODE>
; __device__ __forceinline__ void attn_item(LAS unsigned char* lds, int item, const AttnCtx& cx) {
;     ...
; #pragma unroll
;             for (int d = 0; d < NDV; ++d)
; #pragma unroll
;                 for (int g4 = 0; g4 < 4; ++g4) {
;                     const int dv = 32 * d + 8 * g4 + 4 * h;
;                     const f32x4 gn = *(const f32x4*)(cx.subln + dv);
;                     const u32x2 sz = *(const u32x2*)(P + (size_t)qtok * NIN + COL_Z + head * 128 + dv);
;                     u32x2 o;
;                     o.x = pk2(O[d][4 * g4] * rstd * gn[0] * bflo(sz.x), O[d][4 * g4 + 1] * rstd * gn[1] * bfhi(sz.x));
;                     o.y = pk2(O[d][4 * g4 + 2] * rstd * gn[2] * bflo(sz.y), O[d][4 * g4 + 3] * rstd * gn[3] * bfhi(sz.y));
;                     *(u32x2*)(cx.T + (size_t)qtok * 512 + head * 128 + dv) = o;
;                 }
	v_pk_mul_f32 v[214:215], v[214:215], v[40:41]
	v_pk_mul_f32 v[216:217], v[216:217], v[42:43]
	v_pk_mul_f32 v[214:215], v[214:215], v[38:39]
	v_pk_mul_f32 v[12:13], v[216:217], v[12:13]
	v_cvt_pk_bf16_f32 v214, v214, v215
	v_cvt_pk_bf16_f32 v215, v12, v13
	global_store_dwordx2 v[10:11], v[214:215], off offset:96
	s_nop 0
	v_pk_mul_f32 v[40:41], v[46:47], v[0:1] op_sel_hi:[1,0]
	v_pk_mul_f32 v[42:43], v[48:49], v[0:1] op_sel_hi:[1,0]
	s_waitcnt vmcnt(22)
	v_lshlrev_b32_e32 v38, 16, v168
	v_and_b32_e32 v39, 0xffff0000, v168
	v_lshlrev_b32_e32 v36, 16, v169
	v_and_b32_e32 v37, 0xffff0000, v169
	s_waitcnt vmcnt(21)
	v_pk_mul_f32 v[222:223], v[222:223], v[40:41]
	v_pk_mul_f32 v[224:225], v[224:225], v[42:43]
	v_pk_mul_f32 v[222:223], v[222:223], v[38:39]
	v_pk_mul_f32 v[224:225], v[224:225], v[36:37]
	v_cvt_pk_bf16_f32 v222, v222, v223
	v_cvt_pk_bf16_f32 v223, v224, v225
	global_store_dwordx2 v[10:11], v[222:223], off offset:112
	s_nop 0
	v_pk_mul_f32 v[40:41], v[94:95], v[0:1] op_sel_hi:[1,0]
	v_pk_mul_f32 v[42:43], v[96:97], v[0:1] op_sel_hi:[1,0]
	s_waitcnt vmcnt(21)
	v_lshlrev_b32_e32 v38, 16, v170
	v_and_b32_e32 v39, 0xffff0000, v170
	v_lshlrev_b32_e32 v12, 16, v171
	v_and_b32_e32 v13, 0xffff0000, v171
	s_waitcnt vmcnt(20)
	v_pk_mul_f32 v[226:227], v[226:227], v[40:41]
	v_pk_mul_f32 v[228:229], v[228:229], v[42:43]
	v_pk_mul_f32 v[226:227], v[226:227], v[38:39]
	v_pk_mul_f32 v[12:13], v[228:229], v[12:13]
	v_cvt_pk_bf16_f32 v226, v226, v227
	v_cvt_pk_bf16_f32 v227, v12, v13
	global_store_dwordx2 v[10:11], v[226:227], off offset:128
	s_nop 0
	v_pk_mul_f32 v[40:41], v[90:91], v[0:1] op_sel_hi:[1,0]
	s_waitcnt vmcnt(20)
	v_lshlrev_b32_e32 v38, 16, v172
	v_and_b32_e32 v39, 0xffff0000, v172
	v_lshlrev_b32_e32 v36, 16, v173
	v_and_b32_e32 v37, 0xffff0000, v173
	s_waitcnt vmcnt(19)
	v_pk_mul_f32 v[230:231], v[230:231], v[40:41]
	v_pk_mul_f32 v[232:233], v[232:233], v[34:35]
	v_pk_mul_f32 v[230:231], v[230:231], v[38:39]
	v_pk_mul_f32 v[232:233], v[232:233], v[36:37]
	v_cvt_pk_bf16_f32 v230, v230, v231
	v_cvt_pk_bf16_f32 v231, v232, v233
	global_store_dwordx2 v[10:11], v[230:231], off offset:144
	s_nop 0
	s_waitcnt vmcnt(19)
	v_lshlrev_b32_e32 v36, 16, v174
	v_and_b32_e32 v37, 0xffff0000, v174
	v_lshlrev_b32_e32 v12, 16, v175
	v_and_b32_e32 v13, 0xffff0000, v175
	s_waitcnt vmcnt(18)
	v_pk_mul_f32 v[26:27], v[234:235], v[26:27]
	v_pk_mul_f32 v[28:29], v[236:237], v[28:29]
	v_pk_mul_f32 v[26:27], v[26:27], v[36:37]
	v_pk_mul_f32 v[12:13], v[28:29], v[12:13]
	v_cvt_pk_bf16_f32 v26, v26, v27
	v_cvt_pk_bf16_f32 v27, v12, v13
	global_store_dwordx2 v[10:11], v[26:27], off offset:160
	s_nop 0
	s_waitcnt vmcnt(18)
	v_lshlrev_b32_e32 v30, 16, v176
	v_and_b32_e32 v31, 0xffff0000, v176
	v_lshlrev_b32_e32 v32, 16, v177
	v_and_b32_e32 v33, 0xffff0000, v177
	s_waitcnt vmcnt(17)
	v_pk_mul_f32 v[24:25], v[238:239], v[24:25]
	v_pk_mul_f32 v[22:23], v[240:241], v[22:23]
	v_pk_mul_f32 v[24:25], v[24:25], v[30:31]
	v_pk_mul_f32 v[22:23], v[22:23], v[32:33]
	v_cvt_pk_bf16_f32 v24, v24, v25
	v_cvt_pk_bf16_f32 v25, v22, v23
	global_store_dwordx2 v[10:11], v[24:25], off offset:176
	s_nop 0
	s_waitcnt vmcnt(17)
	v_lshlrev_b32_e32 v28, 16, v184
	v_and_b32_e32 v29, 0xffff0000, v184
	v_lshlrev_b32_e32 v12, 16, v185
	v_and_b32_e32 v13, 0xffff0000, v185
	s_waitcnt vmcnt(16)
	v_pk_mul_f32 v[20:21], v[242:243], v[20:21]
	v_pk_mul_f32 v[18:19], v[244:245], v[18:19]
	v_pk_mul_f32 v[20:21], v[20:21], v[28:29]
	v_pk_mul_f32 v[12:13], v[18:19], v[12:13]
	v_cvt_pk_bf16_f32 v18, v20, v21
	v_cvt_pk_bf16_f32 v19, v12, v13
	global_store_dwordx2 v[10:11], v[18:19], off offset:192
	s_nop 0
	s_waitcnt vmcnt(16)
	v_lshlrev_b32_e32 v22, 16, v186
	v_and_b32_e32 v23, 0xffff0000, v186
	v_lshlrev_b32_e32 v24, 16, v187
	v_and_b32_e32 v25, 0xffff0000, v187
	s_waitcnt vmcnt(15)
	v_pk_mul_f32 v[4:5], v[246:247], v[4:5]
	v_pk_mul_f32 v[2:3], v[248:249], v[2:3]
	v_pk_mul_f32 v[4:5], v[4:5], v[22:23]
	v_pk_mul_f32 v[2:3], v[2:3], v[24:25]
	v_cvt_pk_bf16_f32 v4, v4, v5
	v_cvt_pk_bf16_f32 v5, v2, v3
	global_store_dwordx2 v[10:11], v[4:5], off offset:208
	global_load_dwordx4 v[2:5], v137, s[0:1] offset:448
	s_nop 0
	s_waitcnt vmcnt(16)
	v_lshlrev_b32_e32 v20, 16, v188
	v_and_b32_e32 v21, 0xffff0000, v188
	v_lshlrev_b32_e32 v12, 16, v189
	v_and_b32_e32 v13, 0xffff0000, v189
	s_waitcnt vmcnt(0)
	v_pk_mul_f32 v[2:3], v[2:3], v[8:9]
	v_pk_mul_f32 v[4:5], v[4:5], v[6:7]
	v_pk_mul_f32 v[2:3], v[2:3], v[20:21]
	v_pk_mul_f32 v[4:5], v[4:5], v[12:13]
	v_cvt_pk_bf16_f32 v2, v2, v3
	v_cvt_pk_bf16_f32 v3, v4, v5
	global_store_dwordx2 v[10:11], v[2:3], off offset:224
	global_load_dwordx4 v[2:5], v137, s[0:1] offset:480
	v_pk_mul_f32 v[12:13], v[14:15], v[0:1] op_sel_hi:[1,0]
	v_pk_mul_f32 v[14:15], v[16:17], v[0:1] op_sel_hi:[1,0]
	s_waitcnt vmcnt(2)
	v_lshlrev_b32_e32 v6, 16, v190
	v_and_b32_e32 v7, 0xffff0000, v190
	v_lshlrev_b32_e32 v8, 16, v191
	v_and_b32_e32 v9, 0xffff0000, v191
	s_waitcnt vmcnt(0)
	v_pk_mul_f32 v[2:3], v[2:3], v[12:13]
	v_pk_mul_f32 v[4:5], v[4:5], v[14:15]
	v_pk_mul_f32 v[2:3], v[2:3], v[6:7]
	v_pk_mul_f32 v[4:5], v[4:5], v[8:9]
	v_cvt_pk_bf16_f32 v2, v2, v3
	v_cvt_pk_bf16_f32 v3, v4, v5
	global_store_dwordx2 v[10:11], v[2:3], off offset:240
	s_branch .LBB0_159
